# all four GEMM K loops: last 4 LDS-DMA pieces of the heavy load sections issued inside the following MFMA cluster
# speedup vs baseline: 1.0261x; 1.0023x over previous
.LBB0_365:
	s_add_u32 s10, s60, s8
	s_addc_u32 s11, s61, s9
	s_add_u32 s10, s10, 0x5dc0100
	s_addc_u32 s11, s11, 0
	s_add_u32 s65, s62, s8
	s_addc_u32 s66, s63, s9
	s_add_i32 s67, 0, 0x10000
	s_cmpk_eq_i32 s8, 0x700
	s_cselect_b32 s27, s7, s11
	s_cselect_b32 s26, s6, s10
	s_cselect_b32 s11, s1, s66
	s_cselect_b32 s10, s0, s65
	s_add_i32 s65, 0, 0x14000
	v_add_u32_e32 v144, s67, v122
	v_add_u32_e32 v165, s65, v122
	ds_read_b128 v[124:127], v144
	ds_read_b128 v[128:131], v144 offset:1024
	ds_read_b128 v[132:135], v144 offset:2048
	ds_read_b128 v[144:147], v144 offset:3072
	ds_read_b128 v[148:151], v165
	ds_read_b128 v[160:163], v165 offset:1024
	ds_read_b128 v[166:169], v165 offset:2048
	ds_read_b128 v[170:173], v165 offset:3072
	v_lshl_add_u64 v[206:207], v[110:111], 0, s[8:9]
	s_add_i32 m0, s23, 0xc000
	ds_read_b128 v[174:177], v123
	ds_read_b128 v[178:181], v123 offset:1024
	ds_read_b128 v[182:185], v123 offset:2048
	ds_read_b128 v[186:189], v123 offset:3072
	ds_read_b128 v[190:193], v123 offset:4096
	ds_read_b128 v[194:197], v123 offset:5120
	ds_read_b128 v[198:201], v123 offset:6144
	ds_read_b128 v[202:205], v123 offset:7168
	global_load_lds_dwordx4 v[206:207], off
	v_lshl_add_u64 v[206:207], v[120:121], 0, s[8:9]
	s_add_i32 m0, s23, 0xe000
	s_nop 0
	global_load_lds_dwordx4 v[206:207], off
	s_waitcnt vmcnt(8)
	s_waitcnt lgkmcnt(0)
	s_barrier
	s_setprio 1
	s_waitcnt lgkmcnt(0)
	v_mfma_f32_16x16x32_bf16 v[156:159], v[124:127], v[174:177], v[156:159]
	v_mfma_f32_16x16x32_bf16 v[152:155], v[132:135], v[174:177], v[152:155]
	v_mfma_f32_16x16x32_bf16 v[116:119], v[124:127], v[182:185], v[116:119]
	v_mfma_f32_16x16x32_bf16 v[112:115], v[132:135], v[182:185], v[112:115]
	v_mfma_f32_16x16x32_bf16 v[92:95], v[124:127], v[190:193], v[92:95]
	v_mfma_f32_16x16x32_bf16 v[88:91], v[132:135], v[190:193], v[88:91]
	v_mfma_f32_16x16x32_bf16 v[76:79], v[124:127], v[198:201], v[76:79]
	v_mfma_f32_16x16x32_bf16 v[72:75], v[132:135], v[198:201], v[72:75]
	v_mfma_f32_16x16x32_bf16 v[156:159], v[128:131], v[178:181], v[156:159]
	v_mfma_f32_16x16x32_bf16 v[152:155], v[144:147], v[178:181], v[152:155]
	v_mfma_f32_16x16x32_bf16 v[116:119], v[128:131], v[186:189], v[116:119]
	v_mfma_f32_16x16x32_bf16 v[112:115], v[144:147], v[186:189], v[112:115]
	v_mfma_f32_16x16x32_bf16 v[92:95], v[128:131], v[194:197], v[92:95]
	v_mfma_f32_16x16x32_bf16 v[88:91], v[144:147], v[194:197], v[88:91]
	v_mfma_f32_16x16x32_bf16 v[76:79], v[128:131], v[202:205], v[76:79]
	v_mfma_f32_16x16x32_bf16 v[72:75], v[144:147], v[202:205], v[72:75]
	s_setprio 0
	s_setprio 1
	v_mfma_f32_16x16x32_bf16 v[140:143], v[148:151], v[174:177], v[140:143]
	v_mfma_f32_16x16x32_bf16 v[136:139], v[166:169], v[174:177], v[136:139]
	v_mfma_f32_16x16x32_bf16 v[104:107], v[148:151], v[182:185], v[104:107]
	v_mfma_f32_16x16x32_bf16 v[96:99], v[166:169], v[182:185], v[96:99]
	v_mfma_f32_16x16x32_bf16 v[84:87], v[148:151], v[190:193], v[84:87]
	v_mfma_f32_16x16x32_bf16 v[80:83], v[166:169], v[190:193], v[80:83]
	v_mfma_f32_16x16x32_bf16 v[68:71], v[148:151], v[198:201], v[68:71]
	v_mfma_f32_16x16x32_bf16 v[64:67], v[166:169], v[198:201], v[64:67]
	v_mfma_f32_16x16x32_bf16 v[140:143], v[160:163], v[178:181], v[140:143]
	v_mfma_f32_16x16x32_bf16 v[136:139], v[170:173], v[178:181], v[136:139]
	v_mfma_f32_16x16x32_bf16 v[104:107], v[160:163], v[186:189], v[104:107]
	v_mfma_f32_16x16x32_bf16 v[96:99], v[170:173], v[186:189], v[96:99]
	v_mfma_f32_16x16x32_bf16 v[84:87], v[160:163], v[194:197], v[84:87]
	v_mfma_f32_16x16x32_bf16 v[80:83], v[170:173], v[194:197], v[80:83]
	v_mfma_f32_16x16x32_bf16 v[68:71], v[160:163], v[202:205], v[68:71]
	v_mfma_f32_16x16x32_bf16 v[64:67], v[170:173], v[202:205], v[64:67]
	s_setprio 0
	s_barrier
	s_add_i32 s66, s67, s48
	s_mov_b32 m0, s66
	ds_read_b128 v[174:177], v123 offset:16384
	ds_read_b128 v[178:181], v123 offset:17408
	ds_read_b128 v[182:185], v123 offset:18432
	ds_read_b128 v[186:189], v123 offset:19456
	ds_read_b128 v[190:193], v123 offset:20480
	ds_read_b128 v[194:197], v123 offset:21504
	ds_read_b128 v[198:201], v123 offset:22528
	ds_read_b128 v[202:205], v123 offset:23552
	global_load_lds_dwordx4 v212, s[10:11]
	s_add_i32 m0, s66, 0x2000
	s_add_u32 s66, s10, 0x40000
	s_addc_u32 s67, s11, 0
	s_add_i32 s65, s65, s48
	global_load_lds_dwordx4 v100, s[10:11]


	s_add_u32 s86, s26, s34
	s_addc_u32 s87, s27, s35
	s_add_u32 s84, s10, s34
	s_addc_u32 s85, s11, s35
	s_waitcnt vmcnt(4)
	s_waitcnt lgkmcnt(0)
	s_barrier
	s_setprio 1
	s_waitcnt lgkmcnt(0)
	v_mfma_f32_16x16x32_bf16 v[60:63], v[124:127], v[174:177], v[60:63]
	v_mfma_f32_16x16x32_bf16 v[56:59], v[132:135], v[174:177], v[56:59]
	v_mfma_f32_16x16x32_bf16 v[44:47], v[124:127], v[182:185], v[44:47]
	v_mfma_f32_16x16x32_bf16 v[40:43], v[132:135], v[182:185], v[40:43]
	s_mov_b32 m0, s65
	v_mfma_f32_16x16x32_bf16 v[28:31], v[124:127], v[190:193], v[28:31]
	global_load_lds_dwordx4 v212, s[66:67]
	v_mfma_f32_16x16x32_bf16 v[24:27], v[132:135], v[190:193], v[24:27]
	v_mfma_f32_16x16x32_bf16 v[12:15], v[124:127], v[198:201], v[12:15]
	v_mfma_f32_16x16x32_bf16 v[8:11], v[132:135], v[198:201], v[8:11]
	v_mfma_f32_16x16x32_bf16 v[60:63], v[128:131], v[178:181], v[60:63]
	v_mfma_f32_16x16x32_bf16 v[56:59], v[144:147], v[178:181], v[56:59]
	v_mfma_f32_16x16x32_bf16 v[44:47], v[128:131], v[186:189], v[44:47]
	v_mfma_f32_16x16x32_bf16 v[40:43], v[144:147], v[186:189], v[40:43]
	s_add_i32 m0, s65, 0x2000
	v_mfma_f32_16x16x32_bf16 v[28:31], v[128:131], v[194:197], v[28:31]
	global_load_lds_dwordx4 v100, s[66:67]
	v_mfma_f32_16x16x32_bf16 v[24:27], v[144:147], v[194:197], v[24:27]
	v_mfma_f32_16x16x32_bf16 v[12:15], v[128:131], v[202:205], v[12:15]
	v_mfma_f32_16x16x32_bf16 v[8:11], v[144:147], v[202:205], v[8:11]
	s_setprio 0
	s_setprio 1
	v_mfma_f32_16x16x32_bf16 v[52:55], v[148:151], v[174:177], v[52:55]
	v_mfma_f32_16x16x32_bf16 v[48:51], v[166:169], v[174:177], v[48:51]
	v_mfma_f32_16x16x32_bf16 v[36:39], v[148:151], v[182:185], v[36:39]
	v_mfma_f32_16x16x32_bf16 v[32:35], v[166:169], v[182:185], v[32:35]
	s_mov_b32 m0, s23
	v_mfma_f32_16x16x32_bf16 v[20:23], v[148:151], v[190:193], v[20:23]
	global_load_lds_dwordx4 v108, s[26:27]
	v_mfma_f32_16x16x32_bf16 v[16:19], v[166:169], v[190:193], v[16:19]
	v_mfma_f32_16x16x32_bf16 v[4:7], v[148:151], v[198:201], v[4:7]
	v_mfma_f32_16x16x32_bf16 v[0:3], v[166:169], v[198:201], v[0:3]
	v_mfma_f32_16x16x32_bf16 v[52:55], v[160:163], v[178:181], v[52:55]
	v_mfma_f32_16x16x32_bf16 v[48:51], v[170:173], v[178:181], v[48:51]
	v_mfma_f32_16x16x32_bf16 v[36:39], v[160:163], v[186:189], v[36:39]
	v_mfma_f32_16x16x32_bf16 v[32:35], v[170:173], v[186:189], v[32:35]
	s_mov_b32 m0, s49
	v_mfma_f32_16x16x32_bf16 v[20:23], v[160:163], v[194:197], v[20:23]
	global_load_lds_dwordx4 v102, s[26:27]
	v_mfma_f32_16x16x32_bf16 v[16:19], v[170:173], v[194:197], v[16:19]
	v_mfma_f32_16x16x32_bf16 v[4:7], v[160:163], v[202:205], v[4:7]
	v_mfma_f32_16x16x32_bf16 v[0:3], v[170:173], v[202:205], v[0:3]
	s_setprio 0
	s_barrier
	s_add_i32 s65, 0, 0x18000
	s_add_i32 s66, 0, 0x1c000
	v_add_u32_e32 v144, s65, v122
	v_add_u32_e32 v165, s66, v122
	ds_read_b128 v[124:127], v144
	ds_read_b128 v[128:131], v144 offset:1024
	ds_read_b128 v[132:135], v144 offset:2048
	ds_read_b128 v[144:147], v144 offset:3072
	ds_read_b128 v[148:151], v165
	ds_read_b128 v[160:163], v165 offset:1024
	ds_read_b128 v[166:169], v165 offset:2048
	ds_read_b128 v[170:173], v165 offset:3072
	s_add_u32 s26, s26, 0x40000
	s_addc_u32 s27, s27, 0
	s_mov_b32 m0, s50
	ds_read_b128 v[174:177], v123 offset:32768
	ds_read_b128 v[178:181], v123 offset:33792
	ds_read_b128 v[182:185], v123 offset:34816
	ds_read_b128 v[186:189], v123 offset:35840
	ds_read_b128 v[190:193], v123 offset:36864
	ds_read_b128 v[194:197], v123 offset:37888
	ds_read_b128 v[198:201], v123 offset:38912
	ds_read_b128 v[202:205], v123 offset:39936
	global_load_lds_dwordx4 v108, s[26:27]
	s_mov_b32 m0, s51
	s_nop 0
	global_load_lds_dwordx4 v102, s[26:27]
	s_waitcnt vmcnt(8)
	s_waitcnt lgkmcnt(0)
	s_barrier
	s_setprio 1
	s_waitcnt lgkmcnt(0)
	v_mfma_f32_16x16x32_bf16 v[156:159], v[124:127], v[174:177], v[156:159]
	v_mfma_f32_16x16x32_bf16 v[152:155], v[132:135], v[174:177], v[152:155]
	v_mfma_f32_16x16x32_bf16 v[116:119], v[124:127], v[182:185], v[116:119]
	v_mfma_f32_16x16x32_bf16 v[112:115], v[132:135], v[182:185], v[112:115]
	v_mfma_f32_16x16x32_bf16 v[92:95], v[124:127], v[190:193], v[92:95]
	v_mfma_f32_16x16x32_bf16 v[88:91], v[132:135], v[190:193], v[88:91]
	v_mfma_f32_16x16x32_bf16 v[76:79], v[124:127], v[198:201], v[76:79]
	v_mfma_f32_16x16x32_bf16 v[72:75], v[132:135], v[198:201], v[72:75]
	v_mfma_f32_16x16x32_bf16 v[156:159], v[128:131], v[178:181], v[156:159]
	v_mfma_f32_16x16x32_bf16 v[152:155], v[144:147], v[178:181], v[152:155]
	v_mfma_f32_16x16x32_bf16 v[116:119], v[128:131], v[186:189], v[116:119]
	v_mfma_f32_16x16x32_bf16 v[112:115], v[144:147], v[186:189], v[112:115]
	v_mfma_f32_16x16x32_bf16 v[92:95], v[128:131], v[194:197], v[92:95]
	v_mfma_f32_16x16x32_bf16 v[88:91], v[144:147], v[194:197], v[88:91]
	v_mfma_f32_16x16x32_bf16 v[76:79], v[128:131], v[202:205], v[76:79]
	v_mfma_f32_16x16x32_bf16 v[72:75], v[144:147], v[202:205], v[72:75]
	s_setprio 0
	s_setprio 1
	v_mfma_f32_16x16x32_bf16 v[140:143], v[148:151], v[174:177], v[140:143]
	v_mfma_f32_16x16x32_bf16 v[136:139], v[166:169], v[174:177], v[136:139]
	v_mfma_f32_16x16x32_bf16 v[104:107], v[148:151], v[182:185], v[104:107]
	v_mfma_f32_16x16x32_bf16 v[96:99], v[166:169], v[182:185], v[96:99]
	v_mfma_f32_16x16x32_bf16 v[84:87], v[148:151], v[190:193], v[84:87]
	v_mfma_f32_16x16x32_bf16 v[80:83], v[166:169], v[190:193], v[80:83]
	v_mfma_f32_16x16x32_bf16 v[68:71], v[148:151], v[198:201], v[68:71]
	v_mfma_f32_16x16x32_bf16 v[64:67], v[166:169], v[198:201], v[64:67]
	v_mfma_f32_16x16x32_bf16 v[140:143], v[160:163], v[178:181], v[140:143]
	v_mfma_f32_16x16x32_bf16 v[136:139], v[170:173], v[178:181], v[136:139]
	v_mfma_f32_16x16x32_bf16 v[104:107], v[160:163], v[186:189], v[104:107]
	v_mfma_f32_16x16x32_bf16 v[96:99], v[170:173], v[186:189], v[96:99]
	v_mfma_f32_16x16x32_bf16 v[84:87], v[160:163], v[194:197], v[84:87]
	v_mfma_f32_16x16x32_bf16 v[80:83], v[170:173], v[194:197], v[80:83]
	v_mfma_f32_16x16x32_bf16 v[68:71], v[160:163], v[202:205], v[68:71]
	v_mfma_f32_16x16x32_bf16 v[64:67], v[170:173], v[202:205], v[64:67]
	s_setprio 0
	s_barrier
	s_add_i32 s26, s65, s48
	s_mov_b32 m0, s26
	ds_read_b128 v[174:177], v123 offset:49152
	ds_read_b128 v[178:181], v123 offset:50176
	ds_read_b128 v[182:185], v123 offset:51200
	ds_read_b128 v[186:189], v123 offset:52224
	ds_read_b128 v[190:193], v123 offset:53248
	ds_read_b128 v[194:197], v123 offset:54272
	ds_read_b128 v[198:201], v123 offset:55296
	ds_read_b128 v[202:205], v123 offset:56320
	global_load_lds_dwordx4 v212, s[84:85]
	s_add_i32 m0, s26, 0x2000
	s_add_u32 s10, s10, 0x40080
	s_addc_u32 s11, s11, 0
	s_add_i32 s26, s66, s48
	global_load_lds_dwordx4 v100, s[84:85]


	s_waitcnt vmcnt(4)
	s_waitcnt lgkmcnt(0)
	s_barrier
	s_setprio 1
	s_waitcnt lgkmcnt(0)
	v_mfma_f32_16x16x32_bf16 v[60:63], v[124:127], v[174:177], v[60:63]
	v_mfma_f32_16x16x32_bf16 v[56:59], v[132:135], v[174:177], v[56:59]
	v_mfma_f32_16x16x32_bf16 v[44:47], v[124:127], v[182:185], v[44:47]
	v_mfma_f32_16x16x32_bf16 v[40:43], v[132:135], v[182:185], v[40:43]
	s_mov_b32 m0, s26
	v_mfma_f32_16x16x32_bf16 v[28:31], v[124:127], v[190:193], v[28:31]
	global_load_lds_dwordx4 v212, s[10:11]
	v_mfma_f32_16x16x32_bf16 v[24:27], v[132:135], v[190:193], v[24:27]
	v_mfma_f32_16x16x32_bf16 v[12:15], v[124:127], v[198:201], v[12:15]
	v_mfma_f32_16x16x32_bf16 v[8:11], v[132:135], v[198:201], v[8:11]
	v_mfma_f32_16x16x32_bf16 v[60:63], v[128:131], v[178:181], v[60:63]
	v_mfma_f32_16x16x32_bf16 v[56:59], v[144:147], v[178:181], v[56:59]
	v_mfma_f32_16x16x32_bf16 v[44:47], v[128:131], v[186:189], v[44:47]
	v_mfma_f32_16x16x32_bf16 v[40:43], v[144:147], v[186:189], v[40:43]
	s_add_i32 m0, s26, 0x2000
	v_mfma_f32_16x16x32_bf16 v[28:31], v[128:131], v[194:197], v[28:31]
	global_load_lds_dwordx4 v100, s[10:11]
	v_mfma_f32_16x16x32_bf16 v[24:27], v[144:147], v[194:197], v[24:27]
	v_mfma_f32_16x16x32_bf16 v[12:15], v[128:131], v[202:205], v[12:15]
	v_mfma_f32_16x16x32_bf16 v[8:11], v[144:147], v[202:205], v[8:11]
	s_setprio 0
	s_setprio 1
	v_mfma_f32_16x16x32_bf16 v[52:55], v[148:151], v[174:177], v[52:55]
	v_mfma_f32_16x16x32_bf16 v[48:51], v[166:169], v[174:177], v[48:51]
	v_mfma_f32_16x16x32_bf16 v[36:39], v[148:151], v[182:185], v[36:39]
	v_mfma_f32_16x16x32_bf16 v[32:35], v[166:169], v[182:185], v[32:35]
	s_mov_b32 m0, s58
	v_mfma_f32_16x16x32_bf16 v[20:23], v[148:151], v[190:193], v[20:23]
	global_load_lds_dwordx4 v108, s[86:87]
	v_mfma_f32_16x16x32_bf16 v[16:19], v[166:169], v[190:193], v[16:19]
	v_mfma_f32_16x16x32_bf16 v[4:7], v[148:151], v[198:201], v[4:7]
	v_mfma_f32_16x16x32_bf16 v[0:3], v[166:169], v[198:201], v[0:3]
	v_mfma_f32_16x16x32_bf16 v[52:55], v[160:163], v[178:181], v[52:55]
	v_mfma_f32_16x16x32_bf16 v[48:51], v[170:173], v[178:181], v[48:51]
	v_mfma_f32_16x16x32_bf16 v[36:39], v[160:163], v[186:189], v[36:39]
	v_mfma_f32_16x16x32_bf16 v[32:35], v[170:173], v[186:189], v[32:35]
	s_mov_b32 m0, s59
	v_mfma_f32_16x16x32_bf16 v[20:23], v[160:163], v[194:197], v[20:23]
	global_load_lds_dwordx4 v102, s[86:87]
	v_mfma_f32_16x16x32_bf16 v[16:19], v[170:173], v[194:197], v[16:19]
	v_mfma_f32_16x16x32_bf16 v[4:7], v[160:163], v[202:205], v[4:7]
	v_mfma_f32_16x16x32_bf16 v[0:3], v[170:173], v[202:205], v[0:3]
	s_setprio 0
	s_barrier
	s_add_i32 s64, s64, 2
	s_add_u32 s8, s8, 0x100
	s_addc_u32 s9, s9, 0
	s_cmp_lt_u32 s64, 14
	s_cbranch_scc1 .LBB0_365
	s_waitcnt vmcnt(0)
	s_cmpk_gt_u32 s47, 0xff
	s_cbranch_scc1 .LBB0_368
	s_barrier

.LBB0_497:
	s_ashr_i32 s11, s10, 31
	s_lshl_b64 s[22:23], s[10:11], 19
	s_add_u32 s22, s16, s22
	s_addc_u32 s23, s17, s23
	s_and_b64 s[24:25], s[0:1], exec
	s_cselect_b32 s11, s23, s31
	s_cselect_b32 s49, s22, s30
	s_ashr_i32 s9, s8, 31
	s_lshl_b64 s[24:25], s[8:9], 19
	s_add_u32 s24, s33, s24
	s_addc_u32 s25, s34, s25
	s_and_b64 s[50:51], s[0:1], exec
	s_cselect_b32 s9, s25, s29
	s_cselect_b32 s50, s24, s28
	v_lshl_add_u32 v152, s26, 8, v164
	s_add_u32 s26, s30, 0x40080
	v_add_u32_e32 v150, 0x80, v152
	v_add_u32_e32 v148, 0x90, v152
	v_add_u32_e32 v146, 0xa0, v152
	v_add_u32_e32 v144, 0xb0, v152
	s_addc_u32 s27, s31, 0
	v_ashrrev_i32_e32 v153, 31, v152
	v_ashrrev_i32_e32 v151, 31, v150
	v_ashrrev_i32_e32 v149, 31, v148
	v_ashrrev_i32_e32 v147, 31, v146
	v_ashrrev_i32_e32 v145, 31, v144
	s_add_u32 s51, s28, 0x100
	v_lshl_add_u64 v[154:155], v[152:153], 2, s[20:21]
	v_lshl_add_u64 v[156:157], v[150:151], 2, s[20:21]
	v_lshl_add_u64 v[158:159], v[148:149], 2, s[20:21]
	v_lshl_add_u64 v[160:161], v[146:147], 2, s[20:21]
	v_lshl_add_u64 v[162:163], v[144:145], 2, s[20:21]
	s_addc_u32 s52, s29, 0
	s_mov_b32 s53, -2
	s_mov_b64 s[28:29], 0
	v_add_u32_e32 v188, s46, v165
	v_add_u32_e32 v204, s47, v165
	ds_read_b128 v[176:179], v188
	ds_read_b128 v[180:183], v188 offset:1024
	ds_read_b128 v[184:187], v188 offset:2048
	ds_read_b128 v[188:191], v188 offset:3072
	ds_read_b128 v[192:195], v204
	ds_read_b128 v[196:199], v204 offset:1024
	ds_read_b128 v[200:203], v204 offset:2048
	ds_read_b128 v[204:207], v204 offset:3072
	s_add_u32 s30, s26, 0xfffc0080
	s_addc_u32 s31, s27, -1
	s_and_b64 s[28:29], s[28:29], exec
	s_cselect_b32 s31, s11, s31
	s_cselect_b32 s30, s49, s30
	s_cselect_b32 s29, s9, s52
	s_cselect_b32 s28, s50, s51
	s_add_i32 m0, s36, 0xc000
	ds_read_b128 v[208:211], v167
	ds_read_b128 v[212:215], v167 offset:1024
	ds_read_b128 v[216:219], v167 offset:2048
	ds_read_b128 v[220:223], v167 offset:3072
	ds_read_b128 v[224:227], v167 offset:4096
	ds_read_b128 v[230:233], v167 offset:5120
	ds_read_b128 v[234:237], v167 offset:6144
	ds_read_b128 v[238:241], v167 offset:7168
	global_load_lds_dwordx4 v136, s[26:27]
	s_add_i32 m0, s36, 0xe000
	s_nop 0
	global_load_lds_dwordx4 v138, s[26:27]
	s_waitcnt vmcnt(8)
	s_waitcnt lgkmcnt(0)
	s_barrier
	s_setprio 1
	s_waitcnt lgkmcnt(0)
	v_mfma_f32_16x16x32_bf16 v[124:127], v[176:179], v[208:211], 0
	v_mfma_f32_16x16x32_bf16 v[120:123], v[184:187], v[208:211], 0
	v_mfma_f32_16x16x32_bf16 v[108:111], v[176:179], v[216:219], 0
	v_mfma_f32_16x16x32_bf16 v[104:107], v[184:187], v[216:219], 0
	v_mfma_f32_16x16x32_bf16 v[92:95], v[176:179], v[224:227], 0
	v_mfma_f32_16x16x32_bf16 v[88:91], v[184:187], v[224:227], 0
	v_mfma_f32_16x16x32_bf16 v[76:79], v[176:179], v[234:237], 0
	v_mfma_f32_16x16x32_bf16 v[72:75], v[184:187], v[234:237], 0
	v_mfma_f32_16x16x32_bf16 v[124:127], v[180:183], v[212:215], v[124:127]
	v_mfma_f32_16x16x32_bf16 v[120:123], v[188:191], v[212:215], v[120:123]
	v_mfma_f32_16x16x32_bf16 v[108:111], v[180:183], v[220:223], v[108:111]
	v_mfma_f32_16x16x32_bf16 v[104:107], v[188:191], v[220:223], v[104:107]
	v_mfma_f32_16x16x32_bf16 v[92:95], v[180:183], v[230:233], v[92:95]
	v_mfma_f32_16x16x32_bf16 v[88:91], v[188:191], v[230:233], v[88:91]
	v_mfma_f32_16x16x32_bf16 v[76:79], v[180:183], v[238:241], v[76:79]
	v_mfma_f32_16x16x32_bf16 v[72:75], v[188:191], v[238:241], v[72:75]
	s_setprio 0
	s_setprio 1
	v_mfma_f32_16x16x32_bf16 v[116:119], v[192:195], v[208:211], 0
	v_mfma_f32_16x16x32_bf16 v[112:115], v[200:203], v[208:211], 0
	v_mfma_f32_16x16x32_bf16 v[100:103], v[192:195], v[216:219], 0
	v_mfma_f32_16x16x32_bf16 v[96:99], v[200:203], v[216:219], 0
	v_mfma_f32_16x16x32_bf16 v[84:87], v[192:195], v[224:227], 0
	v_mfma_f32_16x16x32_bf16 v[80:83], v[200:203], v[224:227], 0
	v_mfma_f32_16x16x32_bf16 v[68:71], v[192:195], v[234:237], 0
	v_mfma_f32_16x16x32_bf16 v[64:67], v[200:203], v[234:237], 0
	v_mfma_f32_16x16x32_bf16 v[116:119], v[196:199], v[212:215], v[116:119]
	v_mfma_f32_16x16x32_bf16 v[112:115], v[204:207], v[212:215], v[112:115]
	v_mfma_f32_16x16x32_bf16 v[100:103], v[196:199], v[220:223], v[100:103]
	v_mfma_f32_16x16x32_bf16 v[96:99], v[204:207], v[220:223], v[96:99]
	v_mfma_f32_16x16x32_bf16 v[84:87], v[196:199], v[230:233], v[84:87]
	v_mfma_f32_16x16x32_bf16 v[80:83], v[204:207], v[230:233], v[80:83]
	v_mfma_f32_16x16x32_bf16 v[68:71], v[196:199], v[238:241], v[68:71]
	v_mfma_f32_16x16x32_bf16 v[64:67], v[204:207], v[238:241], v[64:67]
	s_setprio 0
	s_barrier
	s_add_i32 s54, s46, s35
	s_mov_b32 m0, s54
	ds_read_b128 v[208:211], v167 offset:16384
	ds_read_b128 v[212:215], v167 offset:17408
	ds_read_b128 v[216:219], v167 offset:18432
	ds_read_b128 v[220:223], v167 offset:19456
	ds_read_b128 v[224:227], v167 offset:20480
	ds_read_b128 v[230:233], v167 offset:21504
	ds_read_b128 v[234:237], v167 offset:22528
	ds_read_b128 v[238:241], v167 offset:23552
	global_load_lds_dwordx4 v130, s[28:29]
	s_add_i32 m0, s54, 0x2000
	s_add_u32 s54, s28, 0x40000
	s_addc_u32 s55, s29, 0
	s_add_i32 s56, s47, s35
	global_load_lds_dwordx4 v134, s[28:29]


	s_add_u32 s86, s30, s4
	s_addc_u32 s87, s31, s5
	s_add_u32 s84, s28, s4
	s_addc_u32 s85, s29, s5
	s_waitcnt vmcnt(4)
	s_waitcnt lgkmcnt(0)
	s_barrier
	s_setprio 1
	s_waitcnt lgkmcnt(0)
	v_mfma_f32_16x16x32_bf16 v[60:63], v[176:179], v[208:211], 0
	v_mfma_f32_16x16x32_bf16 v[56:59], v[184:187], v[208:211], 0
	v_mfma_f32_16x16x32_bf16 v[44:47], v[176:179], v[216:219], 0
	v_mfma_f32_16x16x32_bf16 v[40:43], v[184:187], v[216:219], 0
	s_mov_b32 m0, s56
	v_mfma_f32_16x16x32_bf16 v[28:31], v[176:179], v[224:227], 0
	global_load_lds_dwordx4 v130, s[54:55]
	v_mfma_f32_16x16x32_bf16 v[24:27], v[184:187], v[224:227], 0
	v_mfma_f32_16x16x32_bf16 v[12:15], v[176:179], v[234:237], 0
	v_mfma_f32_16x16x32_bf16 v[8:11], v[184:187], v[234:237], 0
	v_mfma_f32_16x16x32_bf16 v[60:63], v[180:183], v[212:215], v[60:63]
	v_mfma_f32_16x16x32_bf16 v[56:59], v[188:191], v[212:215], v[56:59]
	v_mfma_f32_16x16x32_bf16 v[44:47], v[180:183], v[220:223], v[44:47]
	v_mfma_f32_16x16x32_bf16 v[40:43], v[188:191], v[220:223], v[40:43]
	s_add_i32 m0, s56, 0x2000
	v_mfma_f32_16x16x32_bf16 v[28:31], v[180:183], v[230:233], v[28:31]
	global_load_lds_dwordx4 v134, s[54:55]
	v_mfma_f32_16x16x32_bf16 v[24:27], v[188:191], v[230:233], v[24:27]
	v_mfma_f32_16x16x32_bf16 v[12:15], v[180:183], v[238:241], v[12:15]
	v_mfma_f32_16x16x32_bf16 v[8:11], v[188:191], v[238:241], v[8:11]
	s_setprio 0
	s_setprio 1
	v_mfma_f32_16x16x32_bf16 v[52:55], v[192:195], v[208:211], 0
	v_mfma_f32_16x16x32_bf16 v[48:51], v[200:203], v[208:211], 0
	v_mfma_f32_16x16x32_bf16 v[36:39], v[192:195], v[216:219], 0
	v_mfma_f32_16x16x32_bf16 v[32:35], v[200:203], v[216:219], 0
	s_mov_b32 m0, s36
	v_mfma_f32_16x16x32_bf16 v[20:23], v[192:195], v[224:227], 0
	global_load_lds_dwordx4 v128, s[30:31]
	v_mfma_f32_16x16x32_bf16 v[16:19], v[200:203], v[224:227], 0
	v_mfma_f32_16x16x32_bf16 v[4:7], v[192:195], v[234:237], 0
	v_mfma_f32_16x16x32_bf16 v[0:3], v[200:203], v[234:237], 0
	v_mfma_f32_16x16x32_bf16 v[52:55], v[196:199], v[212:215], v[52:55]
	v_mfma_f32_16x16x32_bf16 v[48:51], v[204:207], v[212:215], v[48:51]
	v_mfma_f32_16x16x32_bf16 v[36:39], v[196:199], v[220:223], v[36:39]
	v_mfma_f32_16x16x32_bf16 v[32:35], v[204:207], v[220:223], v[32:35]
	s_mov_b32 m0, s37
	v_mfma_f32_16x16x32_bf16 v[20:23], v[196:199], v[230:233], v[20:23]
	global_load_lds_dwordx4 v132, s[30:31]
	v_mfma_f32_16x16x32_bf16 v[16:19], v[204:207], v[230:233], v[16:19]
	v_mfma_f32_16x16x32_bf16 v[4:7], v[196:199], v[238:241], v[4:7]
	v_mfma_f32_16x16x32_bf16 v[0:3], v[204:207], v[238:241], v[0:3]
	s_setprio 0
	s_barrier
	s_add_i32 s54, 0, 0x18000
	s_add_i32 s55, 0, 0x1c000
	v_add_u32_e32 v188, s54, v165
	v_add_u32_e32 v204, s55, v165
	ds_read_b128 v[176:179], v188
	ds_read_b128 v[180:183], v188 offset:1024
	ds_read_b128 v[184:187], v188 offset:2048
	ds_read_b128 v[188:191], v188 offset:3072
	ds_read_b128 v[192:195], v204
	ds_read_b128 v[196:199], v204 offset:1024
	ds_read_b128 v[200:203], v204 offset:2048
	ds_read_b128 v[204:207], v204 offset:3072
	s_add_u32 s30, s30, 0x40000
	s_addc_u32 s31, s31, 0
	s_mov_b32 m0, s41
	ds_read_b128 v[208:211], v167 offset:32768
	ds_read_b128 v[212:215], v167 offset:33792
	ds_read_b128 v[216:219], v167 offset:34816
	ds_read_b128 v[220:223], v167 offset:35840
	ds_read_b128 v[224:227], v167 offset:36864
	ds_read_b128 v[230:233], v167 offset:37888
	ds_read_b128 v[234:237], v167 offset:38912
	ds_read_b128 v[238:241], v167 offset:39936
	global_load_lds_dwordx4 v128, s[30:31]
	s_mov_b32 m0, s42
	s_nop 0
	global_load_lds_dwordx4 v132, s[30:31]
	s_waitcnt vmcnt(8)
	s_waitcnt lgkmcnt(0)
	s_barrier
	s_setprio 1
	s_waitcnt lgkmcnt(0)
	v_mfma_f32_16x16x32_bf16 v[124:127], v[176:179], v[208:211], v[124:127]
	v_mfma_f32_16x16x32_bf16 v[120:123], v[184:187], v[208:211], v[120:123]
	v_mfma_f32_16x16x32_bf16 v[108:111], v[176:179], v[216:219], v[108:111]
	v_mfma_f32_16x16x32_bf16 v[104:107], v[184:187], v[216:219], v[104:107]
	v_mfma_f32_16x16x32_bf16 v[92:95], v[176:179], v[224:227], v[92:95]
	v_mfma_f32_16x16x32_bf16 v[88:91], v[184:187], v[224:227], v[88:91]
	v_mfma_f32_16x16x32_bf16 v[76:79], v[176:179], v[234:237], v[76:79]
	v_mfma_f32_16x16x32_bf16 v[72:75], v[184:187], v[234:237], v[72:75]
	v_mfma_f32_16x16x32_bf16 v[124:127], v[180:183], v[212:215], v[124:127]
	v_mfma_f32_16x16x32_bf16 v[120:123], v[188:191], v[212:215], v[120:123]
	v_mfma_f32_16x16x32_bf16 v[108:111], v[180:183], v[220:223], v[108:111]
	v_mfma_f32_16x16x32_bf16 v[104:107], v[188:191], v[220:223], v[104:107]
	v_mfma_f32_16x16x32_bf16 v[92:95], v[180:183], v[230:233], v[92:95]
	v_mfma_f32_16x16x32_bf16 v[88:91], v[188:191], v[230:233], v[88:91]
	v_mfma_f32_16x16x32_bf16 v[76:79], v[180:183], v[238:241], v[76:79]
	v_mfma_f32_16x16x32_bf16 v[72:75], v[188:191], v[238:241], v[72:75]
	s_setprio 0
	s_setprio 1
	v_mfma_f32_16x16x32_bf16 v[116:119], v[192:195], v[208:211], v[116:119]
	v_mfma_f32_16x16x32_bf16 v[112:115], v[200:203], v[208:211], v[112:115]
	v_mfma_f32_16x16x32_bf16 v[100:103], v[192:195], v[216:219], v[100:103]
	v_mfma_f32_16x16x32_bf16 v[96:99], v[200:203], v[216:219], v[96:99]
	v_mfma_f32_16x16x32_bf16 v[84:87], v[192:195], v[224:227], v[84:87]
	v_mfma_f32_16x16x32_bf16 v[80:83], v[200:203], v[224:227], v[80:83]
	v_mfma_f32_16x16x32_bf16 v[68:71], v[192:195], v[234:237], v[68:71]
	v_mfma_f32_16x16x32_bf16 v[64:67], v[200:203], v[234:237], v[64:67]
	v_mfma_f32_16x16x32_bf16 v[116:119], v[196:199], v[212:215], v[116:119]
	v_mfma_f32_16x16x32_bf16 v[112:115], v[204:207], v[212:215], v[112:115]
	v_mfma_f32_16x16x32_bf16 v[100:103], v[196:199], v[220:223], v[100:103]
	v_mfma_f32_16x16x32_bf16 v[96:99], v[204:207], v[220:223], v[96:99]
	v_mfma_f32_16x16x32_bf16 v[84:87], v[196:199], v[230:233], v[84:87]
	v_mfma_f32_16x16x32_bf16 v[80:83], v[204:207], v[230:233], v[80:83]
	v_mfma_f32_16x16x32_bf16 v[68:71], v[196:199], v[238:241], v[68:71]
	v_mfma_f32_16x16x32_bf16 v[64:67], v[204:207], v[238:241], v[64:67]
	s_setprio 0
	s_barrier
	s_add_i32 s30, s54, s35
	s_mov_b32 m0, s30
	ds_read_b128 v[208:211], v167 offset:49152
	ds_read_b128 v[212:215], v167 offset:50176
	ds_read_b128 v[216:219], v167 offset:51200
	ds_read_b128 v[220:223], v167 offset:52224
	ds_read_b128 v[224:227], v167 offset:53248
	ds_read_b128 v[230:233], v167 offset:54272
	ds_read_b128 v[234:237], v167 offset:55296
	ds_read_b128 v[238:241], v167 offset:56320
	global_load_lds_dwordx4 v130, s[84:85]
	s_add_i32 m0, s30, 0x2000
	s_add_u32 s28, s28, 0x40080
	s_addc_u32 s29, s29, 0
	s_add_i32 s30, s55, s35
	global_load_lds_dwordx4 v134, s[84:85]


	s_waitcnt vmcnt(4)
	s_waitcnt lgkmcnt(0)
	s_barrier
	s_setprio 1
	s_waitcnt lgkmcnt(0)
	v_mfma_f32_16x16x32_bf16 v[60:63], v[176:179], v[208:211], v[60:63]
	v_mfma_f32_16x16x32_bf16 v[56:59], v[184:187], v[208:211], v[56:59]
	v_mfma_f32_16x16x32_bf16 v[44:47], v[176:179], v[216:219], v[44:47]
	v_mfma_f32_16x16x32_bf16 v[40:43], v[184:187], v[216:219], v[40:43]
	s_mov_b32 m0, s30
	v_mfma_f32_16x16x32_bf16 v[28:31], v[176:179], v[224:227], v[28:31]
	global_load_lds_dwordx4 v130, s[28:29]
	v_mfma_f32_16x16x32_bf16 v[24:27], v[184:187], v[224:227], v[24:27]
	v_mfma_f32_16x16x32_bf16 v[12:15], v[176:179], v[234:237], v[12:15]
	v_mfma_f32_16x16x32_bf16 v[8:11], v[184:187], v[234:237], v[8:11]
	v_mfma_f32_16x16x32_bf16 v[60:63], v[180:183], v[212:215], v[60:63]
	v_mfma_f32_16x16x32_bf16 v[56:59], v[188:191], v[212:215], v[56:59]
	v_mfma_f32_16x16x32_bf16 v[44:47], v[180:183], v[220:223], v[44:47]
	v_mfma_f32_16x16x32_bf16 v[40:43], v[188:191], v[220:223], v[40:43]
	s_add_i32 m0, s30, 0x2000
	v_mfma_f32_16x16x32_bf16 v[28:31], v[180:183], v[230:233], v[28:31]
	global_load_lds_dwordx4 v134, s[28:29]
	v_mfma_f32_16x16x32_bf16 v[24:27], v[188:191], v[230:233], v[24:27]
	v_mfma_f32_16x16x32_bf16 v[12:15], v[180:183], v[238:241], v[12:15]
	v_mfma_f32_16x16x32_bf16 v[8:11], v[188:191], v[238:241], v[8:11]
	s_setprio 0
	s_setprio 1
	v_mfma_f32_16x16x32_bf16 v[52:55], v[192:195], v[208:211], v[52:55]
	v_mfma_f32_16x16x32_bf16 v[48:51], v[200:203], v[208:211], v[48:51]
	v_mfma_f32_16x16x32_bf16 v[36:39], v[192:195], v[216:219], v[36:39]
	v_mfma_f32_16x16x32_bf16 v[32:35], v[200:203], v[216:219], v[32:35]
	s_mov_b32 m0, s44
	v_mfma_f32_16x16x32_bf16 v[20:23], v[192:195], v[224:227], v[20:23]
	global_load_lds_dwordx4 v128, s[86:87]
	v_mfma_f32_16x16x32_bf16 v[16:19], v[200:203], v[224:227], v[16:19]
	v_mfma_f32_16x16x32_bf16 v[4:7], v[192:195], v[234:237], v[4:7]
	v_mfma_f32_16x16x32_bf16 v[0:3], v[200:203], v[234:237], v[0:3]
	v_mfma_f32_16x16x32_bf16 v[52:55], v[196:199], v[212:215], v[52:55]
	v_mfma_f32_16x16x32_bf16 v[48:51], v[204:207], v[212:215], v[48:51]
	v_mfma_f32_16x16x32_bf16 v[36:39], v[196:199], v[220:223], v[36:39]
	v_mfma_f32_16x16x32_bf16 v[32:35], v[204:207], v[220:223], v[32:35]
	s_mov_b32 m0, s45
	v_mfma_f32_16x16x32_bf16 v[20:23], v[196:199], v[230:233], v[20:23]
	global_load_lds_dwordx4 v132, s[86:87]
	v_mfma_f32_16x16x32_bf16 v[16:19], v[204:207], v[230:233], v[16:19]
	v_mfma_f32_16x16x32_bf16 v[4:7], v[196:199], v[238:241], v[4:7]
	v_mfma_f32_16x16x32_bf16 v[0:3], v[204:207], v[238:241], v[0:3]
	s_setprio 0
	s_barrier
	s_add_i32 s53, s53, 2
	s_add_u32 s26, s26, 0x100
	s_addc_u32 s27, s27, 0
	s_add_u32 s51, s51, 0x100
	s_addc_u32 s52, s52, 0
	s_branch .LBB0_499
.LBB0_498:
	v_add_u32_e32 v188, s46, v165
	v_add_u32_e32 v204, s47, v165
	ds_read_b128 v[176:179], v188
	ds_read_b128 v[180:183], v188 offset:1024
	ds_read_b128 v[184:187], v188 offset:2048
	ds_read_b128 v[188:191], v188 offset:3072
	ds_read_b128 v[192:195], v204
	ds_read_b128 v[196:199], v204 offset:1024
	ds_read_b128 v[200:203], v204 offset:2048
	ds_read_b128 v[204:207], v204 offset:3072
	s_add_u32 s30, s26, 0xfffc0080
	s_addc_u32 s31, s27, -1
	s_and_b64 s[28:29], s[28:29], exec
	s_cselect_b32 s31, s11, s31
	s_cselect_b32 s30, s49, s30
	s_cselect_b32 s29, s9, s52
	s_cselect_b32 s28, s50, s51
	s_add_i32 m0, s36, 0xc000
	ds_read_b128 v[208:211], v167
	ds_read_b128 v[212:215], v167 offset:1024
	ds_read_b128 v[216:219], v167 offset:2048
	ds_read_b128 v[220:223], v167 offset:3072
	ds_read_b128 v[224:227], v167 offset:4096
	ds_read_b128 v[230:233], v167 offset:5120
	ds_read_b128 v[234:237], v167 offset:6144
	ds_read_b128 v[238:241], v167 offset:7168
	global_load_lds_dwordx4 v136, s[26:27]
	s_add_i32 m0, s36, 0xe000
	s_nop 0
	global_load_lds_dwordx4 v138, s[26:27]
	s_waitcnt vmcnt(8)
	s_waitcnt lgkmcnt(0)
	s_barrier
	s_setprio 1
	s_waitcnt lgkmcnt(0)
	v_mfma_f32_16x16x32_bf16 v[124:127], v[176:179], v[208:211], v[124:127]
	v_mfma_f32_16x16x32_bf16 v[120:123], v[184:187], v[208:211], v[120:123]
	v_mfma_f32_16x16x32_bf16 v[108:111], v[176:179], v[216:219], v[108:111]
	v_mfma_f32_16x16x32_bf16 v[104:107], v[184:187], v[216:219], v[104:107]
	v_mfma_f32_16x16x32_bf16 v[92:95], v[176:179], v[224:227], v[92:95]
	v_mfma_f32_16x16x32_bf16 v[88:91], v[184:187], v[224:227], v[88:91]
	v_mfma_f32_16x16x32_bf16 v[76:79], v[176:179], v[234:237], v[76:79]
	v_mfma_f32_16x16x32_bf16 v[72:75], v[184:187], v[234:237], v[72:75]
	v_mfma_f32_16x16x32_bf16 v[124:127], v[180:183], v[212:215], v[124:127]
	v_mfma_f32_16x16x32_bf16 v[120:123], v[188:191], v[212:215], v[120:123]
	v_mfma_f32_16x16x32_bf16 v[108:111], v[180:183], v[220:223], v[108:111]
	v_mfma_f32_16x16x32_bf16 v[104:107], v[188:191], v[220:223], v[104:107]
	v_mfma_f32_16x16x32_bf16 v[92:95], v[180:183], v[230:233], v[92:95]
	v_mfma_f32_16x16x32_bf16 v[88:91], v[188:191], v[230:233], v[88:91]
	v_mfma_f32_16x16x32_bf16 v[76:79], v[180:183], v[238:241], v[76:79]
	v_mfma_f32_16x16x32_bf16 v[72:75], v[188:191], v[238:241], v[72:75]
	s_setprio 0
	s_setprio 1
	v_mfma_f32_16x16x32_bf16 v[116:119], v[192:195], v[208:211], v[116:119]
	v_mfma_f32_16x16x32_bf16 v[112:115], v[200:203], v[208:211], v[112:115]
	v_mfma_f32_16x16x32_bf16 v[100:103], v[192:195], v[216:219], v[100:103]
	v_mfma_f32_16x16x32_bf16 v[96:99], v[200:203], v[216:219], v[96:99]
	v_mfma_f32_16x16x32_bf16 v[84:87], v[192:195], v[224:227], v[84:87]
	v_mfma_f32_16x16x32_bf16 v[80:83], v[200:203], v[224:227], v[80:83]
	v_mfma_f32_16x16x32_bf16 v[68:71], v[192:195], v[234:237], v[68:71]
	v_mfma_f32_16x16x32_bf16 v[64:67], v[200:203], v[234:237], v[64:67]
	v_mfma_f32_16x16x32_bf16 v[116:119], v[196:199], v[212:215], v[116:119]
	v_mfma_f32_16x16x32_bf16 v[112:115], v[204:207], v[212:215], v[112:115]
	v_mfma_f32_16x16x32_bf16 v[100:103], v[196:199], v[220:223], v[100:103]
	v_mfma_f32_16x16x32_bf16 v[96:99], v[204:207], v[220:223], v[96:99]
	v_mfma_f32_16x16x32_bf16 v[84:87], v[196:199], v[230:233], v[84:87]
	v_mfma_f32_16x16x32_bf16 v[80:83], v[204:207], v[230:233], v[80:83]
	v_mfma_f32_16x16x32_bf16 v[68:71], v[196:199], v[238:241], v[68:71]
	v_mfma_f32_16x16x32_bf16 v[64:67], v[204:207], v[238:241], v[64:67]
	s_setprio 0
	s_barrier
	s_add_i32 s54, s46, s35
	s_mov_b32 m0, s54
	ds_read_b128 v[208:211], v167 offset:16384
	ds_read_b128 v[212:215], v167 offset:17408
	ds_read_b128 v[216:219], v167 offset:18432
	ds_read_b128 v[220:223], v167 offset:19456
	ds_read_b128 v[224:227], v167 offset:20480
	ds_read_b128 v[230:233], v167 offset:21504
	ds_read_b128 v[234:237], v167 offset:22528
	ds_read_b128 v[238:241], v167 offset:23552
	global_load_lds_dwordx4 v130, s[28:29]
	s_add_i32 m0, s54, 0x2000
	s_add_u32 s54, s28, 0x40000
	s_addc_u32 s55, s29, 0
	s_add_i32 s56, s47, s35
	global_load_lds_dwordx4 v134, s[28:29]


	s_add_u32 s86, s30, s4
	s_addc_u32 s87, s31, s5
	s_add_u32 s84, s28, s4
	s_addc_u32 s85, s29, s5
	s_waitcnt vmcnt(4)
	s_waitcnt lgkmcnt(0)
	s_barrier
	s_setprio 1
	s_waitcnt lgkmcnt(0)
	v_mfma_f32_16x16x32_bf16 v[60:63], v[176:179], v[208:211], v[60:63]
	v_mfma_f32_16x16x32_bf16 v[56:59], v[184:187], v[208:211], v[56:59]
	v_mfma_f32_16x16x32_bf16 v[44:47], v[176:179], v[216:219], v[44:47]
	v_mfma_f32_16x16x32_bf16 v[40:43], v[184:187], v[216:219], v[40:43]
	s_mov_b32 m0, s56
	v_mfma_f32_16x16x32_bf16 v[28:31], v[176:179], v[224:227], v[28:31]
	global_load_lds_dwordx4 v130, s[54:55]
	v_mfma_f32_16x16x32_bf16 v[24:27], v[184:187], v[224:227], v[24:27]
	v_mfma_f32_16x16x32_bf16 v[12:15], v[176:179], v[234:237], v[12:15]
	v_mfma_f32_16x16x32_bf16 v[8:11], v[184:187], v[234:237], v[8:11]
	v_mfma_f32_16x16x32_bf16 v[60:63], v[180:183], v[212:215], v[60:63]
	v_mfma_f32_16x16x32_bf16 v[56:59], v[188:191], v[212:215], v[56:59]
	v_mfma_f32_16x16x32_bf16 v[44:47], v[180:183], v[220:223], v[44:47]
	v_mfma_f32_16x16x32_bf16 v[40:43], v[188:191], v[220:223], v[40:43]
	s_add_i32 m0, s56, 0x2000
	v_mfma_f32_16x16x32_bf16 v[28:31], v[180:183], v[230:233], v[28:31]
	global_load_lds_dwordx4 v134, s[54:55]
	v_mfma_f32_16x16x32_bf16 v[24:27], v[188:191], v[230:233], v[24:27]
	v_mfma_f32_16x16x32_bf16 v[12:15], v[180:183], v[238:241], v[12:15]
	v_mfma_f32_16x16x32_bf16 v[8:11], v[188:191], v[238:241], v[8:11]
	s_setprio 0
	s_setprio 1
	v_mfma_f32_16x16x32_bf16 v[52:55], v[192:195], v[208:211], v[52:55]
	v_mfma_f32_16x16x32_bf16 v[48:51], v[200:203], v[208:211], v[48:51]
	v_mfma_f32_16x16x32_bf16 v[36:39], v[192:195], v[216:219], v[36:39]
	v_mfma_f32_16x16x32_bf16 v[32:35], v[200:203], v[216:219], v[32:35]
	s_mov_b32 m0, s36
	v_mfma_f32_16x16x32_bf16 v[20:23], v[192:195], v[224:227], v[20:23]
	global_load_lds_dwordx4 v128, s[30:31]
	v_mfma_f32_16x16x32_bf16 v[16:19], v[200:203], v[224:227], v[16:19]
	v_mfma_f32_16x16x32_bf16 v[4:7], v[192:195], v[234:237], v[4:7]
	v_mfma_f32_16x16x32_bf16 v[0:3], v[200:203], v[234:237], v[0:3]
	v_mfma_f32_16x16x32_bf16 v[52:55], v[196:199], v[212:215], v[52:55]
	v_mfma_f32_16x16x32_bf16 v[48:51], v[204:207], v[212:215], v[48:51]
	v_mfma_f32_16x16x32_bf16 v[36:39], v[196:199], v[220:223], v[36:39]
	v_mfma_f32_16x16x32_bf16 v[32:35], v[204:207], v[220:223], v[32:35]
	s_mov_b32 m0, s37
	v_mfma_f32_16x16x32_bf16 v[20:23], v[196:199], v[230:233], v[20:23]
	global_load_lds_dwordx4 v132, s[30:31]
	v_mfma_f32_16x16x32_bf16 v[16:19], v[204:207], v[230:233], v[16:19]
	v_mfma_f32_16x16x32_bf16 v[4:7], v[196:199], v[238:241], v[4:7]
	v_mfma_f32_16x16x32_bf16 v[0:3], v[204:207], v[238:241], v[0:3]
	s_setprio 0
	s_barrier
	s_add_i32 s54, 0, 0x18000
	s_add_i32 s55, 0, 0x1c000
	v_add_u32_e32 v188, s54, v165
	v_add_u32_e32 v204, s55, v165
	ds_read_b128 v[176:179], v188
	ds_read_b128 v[180:183], v188 offset:1024
	ds_read_b128 v[184:187], v188 offset:2048
	ds_read_b128 v[188:191], v188 offset:3072
	ds_read_b128 v[192:195], v204
	ds_read_b128 v[196:199], v204 offset:1024
	ds_read_b128 v[200:203], v204 offset:2048
	ds_read_b128 v[204:207], v204 offset:3072
	s_add_u32 s30, s30, 0x40000
	s_addc_u32 s31, s31, 0
	s_mov_b32 m0, s41
	ds_read_b128 v[208:211], v167 offset:32768
	ds_read_b128 v[212:215], v167 offset:33792
	ds_read_b128 v[216:219], v167 offset:34816
	ds_read_b128 v[220:223], v167 offset:35840
	ds_read_b128 v[224:227], v167 offset:36864
	ds_read_b128 v[230:233], v167 offset:37888
	ds_read_b128 v[234:237], v167 offset:38912
	ds_read_b128 v[238:241], v167 offset:39936
	global_load_lds_dwordx4 v128, s[30:31]
	s_mov_b32 m0, s42
	s_nop 0
	global_load_lds_dwordx4 v132, s[30:31]
	s_waitcnt vmcnt(8)
	s_waitcnt lgkmcnt(0)
	s_barrier
	s_setprio 1
	s_waitcnt lgkmcnt(0)
	v_mfma_f32_16x16x32_bf16 v[124:127], v[176:179], v[208:211], v[124:127]
	v_mfma_f32_16x16x32_bf16 v[120:123], v[184:187], v[208:211], v[120:123]
	v_mfma_f32_16x16x32_bf16 v[108:111], v[176:179], v[216:219], v[108:111]
	v_mfma_f32_16x16x32_bf16 v[104:107], v[184:187], v[216:219], v[104:107]
	v_mfma_f32_16x16x32_bf16 v[92:95], v[176:179], v[224:227], v[92:95]
	v_mfma_f32_16x16x32_bf16 v[88:91], v[184:187], v[224:227], v[88:91]
	v_mfma_f32_16x16x32_bf16 v[76:79], v[176:179], v[234:237], v[76:79]
	v_mfma_f32_16x16x32_bf16 v[72:75], v[184:187], v[234:237], v[72:75]
	v_mfma_f32_16x16x32_bf16 v[124:127], v[180:183], v[212:215], v[124:127]
	v_mfma_f32_16x16x32_bf16 v[120:123], v[188:191], v[212:215], v[120:123]
	v_mfma_f32_16x16x32_bf16 v[108:111], v[180:183], v[220:223], v[108:111]
	v_mfma_f32_16x16x32_bf16 v[104:107], v[188:191], v[220:223], v[104:107]
	v_mfma_f32_16x16x32_bf16 v[92:95], v[180:183], v[230:233], v[92:95]
	v_mfma_f32_16x16x32_bf16 v[88:91], v[188:191], v[230:233], v[88:91]
	v_mfma_f32_16x16x32_bf16 v[76:79], v[180:183], v[238:241], v[76:79]
	v_mfma_f32_16x16x32_bf16 v[72:75], v[188:191], v[238:241], v[72:75]
	s_setprio 0
	s_setprio 1
	v_mfma_f32_16x16x32_bf16 v[116:119], v[192:195], v[208:211], v[116:119]
	v_mfma_f32_16x16x32_bf16 v[112:115], v[200:203], v[208:211], v[112:115]
	v_mfma_f32_16x16x32_bf16 v[100:103], v[192:195], v[216:219], v[100:103]
	v_mfma_f32_16x16x32_bf16 v[96:99], v[200:203], v[216:219], v[96:99]
	v_mfma_f32_16x16x32_bf16 v[84:87], v[192:195], v[224:227], v[84:87]
	v_mfma_f32_16x16x32_bf16 v[80:83], v[200:203], v[224:227], v[80:83]
	v_mfma_f32_16x16x32_bf16 v[68:71], v[192:195], v[234:237], v[68:71]
	v_mfma_f32_16x16x32_bf16 v[64:67], v[200:203], v[234:237], v[64:67]
	v_mfma_f32_16x16x32_bf16 v[116:119], v[196:199], v[212:215], v[116:119]
	v_mfma_f32_16x16x32_bf16 v[112:115], v[204:207], v[212:215], v[112:115]
	v_mfma_f32_16x16x32_bf16 v[100:103], v[196:199], v[220:223], v[100:103]
	v_mfma_f32_16x16x32_bf16 v[96:99], v[204:207], v[220:223], v[96:99]
	v_mfma_f32_16x16x32_bf16 v[84:87], v[196:199], v[230:233], v[84:87]
	v_mfma_f32_16x16x32_bf16 v[80:83], v[204:207], v[230:233], v[80:83]
	v_mfma_f32_16x16x32_bf16 v[68:71], v[196:199], v[238:241], v[68:71]
	v_mfma_f32_16x16x32_bf16 v[64:67], v[204:207], v[238:241], v[64:67]
	s_setprio 0
	s_barrier
	s_add_i32 s30, s54, s35
	s_mov_b32 m0, s30
	ds_read_b128 v[208:211], v167 offset:49152
	ds_read_b128 v[212:215], v167 offset:50176
	ds_read_b128 v[216:219], v167 offset:51200
	ds_read_b128 v[220:223], v167 offset:52224
	ds_read_b128 v[224:227], v167 offset:53248
	ds_read_b128 v[230:233], v167 offset:54272
	ds_read_b128 v[234:237], v167 offset:55296
	ds_read_b128 v[238:241], v167 offset:56320
	global_load_lds_dwordx4 v130, s[84:85]
	s_add_i32 m0, s30, 0x2000
	s_add_u32 s28, s28, 0x40080
	s_addc_u32 s29, s29, 0
	s_add_i32 s30, s55, s35
	global_load_lds_dwordx4 v134, s[84:85]


	s_waitcnt vmcnt(4)
	s_waitcnt lgkmcnt(0)
	s_barrier
	s_setprio 1
	s_waitcnt lgkmcnt(0)
	v_mfma_f32_16x16x32_bf16 v[60:63], v[176:179], v[208:211], v[60:63]
	v_mfma_f32_16x16x32_bf16 v[56:59], v[184:187], v[208:211], v[56:59]
	v_mfma_f32_16x16x32_bf16 v[44:47], v[176:179], v[216:219], v[44:47]
	v_mfma_f32_16x16x32_bf16 v[40:43], v[184:187], v[216:219], v[40:43]
	s_mov_b32 m0, s30
	v_mfma_f32_16x16x32_bf16 v[28:31], v[176:179], v[224:227], v[28:31]
	global_load_lds_dwordx4 v130, s[28:29]
	v_mfma_f32_16x16x32_bf16 v[24:27], v[184:187], v[224:227], v[24:27]
	v_mfma_f32_16x16x32_bf16 v[12:15], v[176:179], v[234:237], v[12:15]
	v_mfma_f32_16x16x32_bf16 v[8:11], v[184:187], v[234:237], v[8:11]
	v_mfma_f32_16x16x32_bf16 v[60:63], v[180:183], v[212:215], v[60:63]
	v_mfma_f32_16x16x32_bf16 v[56:59], v[188:191], v[212:215], v[56:59]
	v_mfma_f32_16x16x32_bf16 v[44:47], v[180:183], v[220:223], v[44:47]
	v_mfma_f32_16x16x32_bf16 v[40:43], v[188:191], v[220:223], v[40:43]
	s_add_i32 m0, s30, 0x2000
	v_mfma_f32_16x16x32_bf16 v[28:31], v[180:183], v[230:233], v[28:31]
	global_load_lds_dwordx4 v134, s[28:29]
	v_mfma_f32_16x16x32_bf16 v[24:27], v[188:191], v[230:233], v[24:27]
	v_mfma_f32_16x16x32_bf16 v[12:15], v[180:183], v[238:241], v[12:15]
	v_mfma_f32_16x16x32_bf16 v[8:11], v[188:191], v[238:241], v[8:11]
	s_setprio 0
	s_setprio 1
	v_mfma_f32_16x16x32_bf16 v[52:55], v[192:195], v[208:211], v[52:55]
	v_mfma_f32_16x16x32_bf16 v[48:51], v[200:203], v[208:211], v[48:51]
	v_mfma_f32_16x16x32_bf16 v[36:39], v[192:195], v[216:219], v[36:39]
	v_mfma_f32_16x16x32_bf16 v[32:35], v[200:203], v[216:219], v[32:35]
	s_mov_b32 m0, s44
	v_mfma_f32_16x16x32_bf16 v[20:23], v[192:195], v[224:227], v[20:23]
	global_load_lds_dwordx4 v128, s[86:87]
	v_mfma_f32_16x16x32_bf16 v[16:19], v[200:203], v[224:227], v[16:19]
	v_mfma_f32_16x16x32_bf16 v[4:7], v[192:195], v[234:237], v[4:7]
	v_mfma_f32_16x16x32_bf16 v[0:3], v[200:203], v[234:237], v[0:3]
	v_mfma_f32_16x16x32_bf16 v[52:55], v[196:199], v[212:215], v[52:55]
	v_mfma_f32_16x16x32_bf16 v[48:51], v[204:207], v[212:215], v[48:51]
	v_mfma_f32_16x16x32_bf16 v[36:39], v[196:199], v[220:223], v[36:39]
	v_mfma_f32_16x16x32_bf16 v[32:35], v[204:207], v[220:223], v[32:35]
	s_mov_b32 m0, s45
	v_mfma_f32_16x16x32_bf16 v[20:23], v[196:199], v[230:233], v[20:23]
	global_load_lds_dwordx4 v132, s[86:87]
	v_mfma_f32_16x16x32_bf16 v[16:19], v[204:207], v[230:233], v[16:19]
	v_mfma_f32_16x16x32_bf16 v[4:7], v[196:199], v[238:241], v[4:7]
	v_mfma_f32_16x16x32_bf16 v[0:3], v[204:207], v[238:241], v[0:3]
	s_setprio 0
	s_barrier
	s_add_i32 s53, s53, 2
	s_add_u32 s26, s26, 0x100
	s_addc_u32 s27, s27, 0
	s_add_u32 s51, s51, 0x100
	s_addc_u32 s52, s52, 0
	s_cmp_gt_u32 s53, 13
	s_cbranch_scc1 .LBB0_501

.LBB0_599:
	s_add_u32 s20, s50, s18
	s_addc_u32 s21, s51, s19
	s_add_u32 s20, s20, 0x1d80100
	s_addc_u32 s21, s21, 0
	s_add_u32 s55, s52, s18
	s_addc_u32 s56, s53, s19
	s_add_i32 s57, 0, 0x10000
	s_cmpk_eq_i32 s18, 0x1f00
	s_cselect_b32 s23, s11, s21
	s_cselect_b32 s22, s10, s20
	s_cselect_b32 s21, s1, s56
	s_cselect_b32 s20, s0, s55
	s_add_i32 s55, 0, 0x14000
	v_add_u32_e32 v152, s57, v138
	v_add_u32_e32 v168, s55, v138
	ds_read_b128 v[140:143], v152
	ds_read_b128 v[144:147], v152 offset:1024
	ds_read_b128 v[148:151], v152 offset:2048
	ds_read_b128 v[152:155], v152 offset:3072
	ds_read_b128 v[156:159], v168
	ds_read_b128 v[160:163], v168 offset:1024
	ds_read_b128 v[164:167], v168 offset:2048
	ds_read_b128 v[168:171], v168 offset:3072
	v_lshl_add_u64 v[180:181], v[134:135], 0, s[18:19]
	s_add_i32 m0, s43, 0xc000
	ds_read_b128 v[172:175], v139
	ds_read_b128 v[176:179], v139 offset:1024
	ds_read_b128 v[184:187], v139 offset:2048
	ds_read_b128 v[188:191], v139 offset:3072
	ds_read_b128 v[192:195], v139 offset:4096
	ds_read_b128 v[196:199], v139 offset:5120
	ds_read_b128 v[200:203], v139 offset:6144
	ds_read_b128 v[204:207], v139 offset:7168
	global_load_lds_dwordx4 v[180:181], off
	v_lshl_add_u64 v[180:181], v[136:137], 0, s[18:19]
	s_add_i32 m0, s43, 0xe000
	s_nop 0
	global_load_lds_dwordx4 v[180:181], off
	s_waitcnt vmcnt(8)
	s_waitcnt lgkmcnt(0)
	s_barrier
	s_setprio 1
	s_waitcnt lgkmcnt(0)
	v_mfma_f32_16x16x32_bf16 v[124:127], v[140:143], v[172:175], v[124:127]
	v_mfma_f32_16x16x32_bf16 v[120:123], v[148:151], v[172:175], v[120:123]
	v_mfma_f32_16x16x32_bf16 v[116:119], v[140:143], v[184:187], v[116:119]
	v_mfma_f32_16x16x32_bf16 v[112:115], v[148:151], v[184:187], v[112:115]
	v_mfma_f32_16x16x32_bf16 v[92:95], v[140:143], v[192:195], v[92:95]
	v_mfma_f32_16x16x32_bf16 v[88:91], v[148:151], v[192:195], v[88:91]
	v_mfma_f32_16x16x32_bf16 v[80:83], v[140:143], v[200:203], v[80:83]
	v_mfma_f32_16x16x32_bf16 v[72:75], v[148:151], v[200:203], v[72:75]
	v_mfma_f32_16x16x32_bf16 v[124:127], v[144:147], v[176:179], v[124:127]
	v_mfma_f32_16x16x32_bf16 v[120:123], v[152:155], v[176:179], v[120:123]
	v_mfma_f32_16x16x32_bf16 v[116:119], v[144:147], v[188:191], v[116:119]
	v_mfma_f32_16x16x32_bf16 v[112:115], v[152:155], v[188:191], v[112:115]
	v_mfma_f32_16x16x32_bf16 v[92:95], v[144:147], v[196:199], v[92:95]
	v_mfma_f32_16x16x32_bf16 v[88:91], v[152:155], v[196:199], v[88:91]
	v_mfma_f32_16x16x32_bf16 v[80:83], v[144:147], v[204:207], v[80:83]
	v_mfma_f32_16x16x32_bf16 v[72:75], v[152:155], v[204:207], v[72:75]
	s_setprio 0
	s_setprio 1
	v_mfma_f32_16x16x32_bf16 v[108:111], v[156:159], v[172:175], v[108:111]
	v_mfma_f32_16x16x32_bf16 v[104:107], v[164:167], v[172:175], v[104:107]
	v_mfma_f32_16x16x32_bf16 v[100:103], v[156:159], v[184:187], v[100:103]
	v_mfma_f32_16x16x32_bf16 v[96:99], v[164:167], v[184:187], v[96:99]
	v_mfma_f32_16x16x32_bf16 v[84:87], v[156:159], v[192:195], v[84:87]
	v_mfma_f32_16x16x32_bf16 v[76:79], v[164:167], v[192:195], v[76:79]
	v_mfma_f32_16x16x32_bf16 v[68:71], v[156:159], v[200:203], v[68:71]
	v_mfma_f32_16x16x32_bf16 v[64:67], v[164:167], v[200:203], v[64:67]
	v_mfma_f32_16x16x32_bf16 v[108:111], v[160:163], v[176:179], v[108:111]
	v_mfma_f32_16x16x32_bf16 v[104:107], v[168:171], v[176:179], v[104:107]
	v_mfma_f32_16x16x32_bf16 v[100:103], v[160:163], v[188:191], v[100:103]
	v_mfma_f32_16x16x32_bf16 v[96:99], v[168:171], v[188:191], v[96:99]
	v_mfma_f32_16x16x32_bf16 v[84:87], v[160:163], v[196:199], v[84:87]
	v_mfma_f32_16x16x32_bf16 v[76:79], v[168:171], v[196:199], v[76:79]
	v_mfma_f32_16x16x32_bf16 v[68:71], v[160:163], v[204:207], v[68:71]
	v_mfma_f32_16x16x32_bf16 v[64:67], v[168:171], v[204:207], v[64:67]
	s_setprio 0
	s_barrier
	s_add_i32 s56, s57, s42
	s_mov_b32 m0, s56
	ds_read_b128 v[172:175], v139 offset:16384
	ds_read_b128 v[176:179], v139 offset:17408
	ds_read_b128 v[184:187], v139 offset:18432
	ds_read_b128 v[188:191], v139 offset:19456
	ds_read_b128 v[192:195], v139 offset:20480
	ds_read_b128 v[196:199], v139 offset:21504
	ds_read_b128 v[200:203], v139 offset:22528
	ds_read_b128 v[204:207], v139 offset:23552
	global_load_lds_dwordx4 v212, s[20:21]
	s_add_i32 m0, s56, 0x2000
	s_add_u32 s56, s20, 0x100000
	s_addc_u32 s57, s21, 0
	s_add_i32 s55, s55, s42
	global_load_lds_dwordx4 v128, s[20:21]


	s_add_u32 s86, s22, s4
	s_addc_u32 s87, s23, s5
	s_add_u32 s84, s20, s4
	s_addc_u32 s85, s21, s5
	s_waitcnt vmcnt(4)
	s_waitcnt lgkmcnt(0)
	s_barrier
	s_setprio 1
	s_waitcnt lgkmcnt(0)
	v_mfma_f32_16x16x32_bf16 v[60:63], v[140:143], v[172:175], v[60:63]
	v_mfma_f32_16x16x32_bf16 v[56:59], v[148:151], v[172:175], v[56:59]
	v_mfma_f32_16x16x32_bf16 v[48:51], v[140:143], v[184:187], v[48:51]
	v_mfma_f32_16x16x32_bf16 v[40:43], v[148:151], v[184:187], v[40:43]
	s_mov_b32 m0, s55
	v_mfma_f32_16x16x32_bf16 v[28:31], v[140:143], v[192:195], v[28:31]
	global_load_lds_dwordx4 v212, s[56:57]
	v_mfma_f32_16x16x32_bf16 v[24:27], v[148:151], v[192:195], v[24:27]
	v_mfma_f32_16x16x32_bf16 v[16:19], v[140:143], v[200:203], v[16:19]
	v_mfma_f32_16x16x32_bf16 v[8:11], v[148:151], v[200:203], v[8:11]
	v_mfma_f32_16x16x32_bf16 v[60:63], v[144:147], v[176:179], v[60:63]
	v_mfma_f32_16x16x32_bf16 v[56:59], v[152:155], v[176:179], v[56:59]
	v_mfma_f32_16x16x32_bf16 v[48:51], v[144:147], v[188:191], v[48:51]
	v_mfma_f32_16x16x32_bf16 v[40:43], v[152:155], v[188:191], v[40:43]
	s_add_i32 m0, s55, 0x2000
	v_mfma_f32_16x16x32_bf16 v[28:31], v[144:147], v[196:199], v[28:31]
	global_load_lds_dwordx4 v128, s[56:57]
	v_mfma_f32_16x16x32_bf16 v[24:27], v[152:155], v[196:199], v[24:27]
	v_mfma_f32_16x16x32_bf16 v[16:19], v[144:147], v[204:207], v[16:19]
	v_mfma_f32_16x16x32_bf16 v[8:11], v[152:155], v[204:207], v[8:11]
	s_setprio 0
	s_setprio 1
	v_mfma_f32_16x16x32_bf16 v[52:55], v[156:159], v[172:175], v[52:55]
	v_mfma_f32_16x16x32_bf16 v[44:47], v[164:167], v[172:175], v[44:47]
	v_mfma_f32_16x16x32_bf16 v[36:39], v[156:159], v[184:187], v[36:39]
	v_mfma_f32_16x16x32_bf16 v[32:35], v[164:167], v[184:187], v[32:35]
	s_mov_b32 m0, s43
	v_mfma_f32_16x16x32_bf16 v[20:23], v[156:159], v[192:195], v[20:23]
	global_load_lds_dwordx4 v132, s[22:23]
	v_mfma_f32_16x16x32_bf16 v[12:15], v[164:167], v[192:195], v[12:15]
	v_mfma_f32_16x16x32_bf16 v[4:7], v[156:159], v[200:203], v[4:7]
	v_mfma_f32_16x16x32_bf16 v[0:3], v[164:167], v[200:203], v[0:3]
	v_mfma_f32_16x16x32_bf16 v[52:55], v[160:163], v[176:179], v[52:55]
	v_mfma_f32_16x16x32_bf16 v[44:47], v[168:171], v[176:179], v[44:47]
	v_mfma_f32_16x16x32_bf16 v[36:39], v[160:163], v[188:191], v[36:39]
	v_mfma_f32_16x16x32_bf16 v[32:35], v[168:171], v[188:191], v[32:35]
	s_mov_b32 m0, s44
	v_mfma_f32_16x16x32_bf16 v[20:23], v[160:163], v[196:199], v[20:23]
	global_load_lds_dwordx4 v130, s[22:23]
	v_mfma_f32_16x16x32_bf16 v[12:15], v[168:171], v[196:199], v[12:15]
	v_mfma_f32_16x16x32_bf16 v[4:7], v[160:163], v[204:207], v[4:7]
	v_mfma_f32_16x16x32_bf16 v[0:3], v[168:171], v[204:207], v[0:3]
	s_setprio 0
	s_barrier
	s_add_i32 s55, 0, 0x18000
	s_add_i32 s56, 0, 0x1c000
	v_add_u32_e32 v152, s55, v138
	v_add_u32_e32 v168, s56, v138
	ds_read_b128 v[140:143], v152
	ds_read_b128 v[144:147], v152 offset:1024
	ds_read_b128 v[148:151], v152 offset:2048
	ds_read_b128 v[152:155], v152 offset:3072
	ds_read_b128 v[156:159], v168
	ds_read_b128 v[160:163], v168 offset:1024
	ds_read_b128 v[164:167], v168 offset:2048
	ds_read_b128 v[168:171], v168 offset:3072
	s_add_u32 s22, s22, 0x100000
	s_addc_u32 s23, s23, 0
	s_mov_b32 m0, s45
	ds_read_b128 v[172:175], v139 offset:32768
	ds_read_b128 v[176:179], v139 offset:33792
	ds_read_b128 v[184:187], v139 offset:34816
	ds_read_b128 v[188:191], v139 offset:35840
	ds_read_b128 v[192:195], v139 offset:36864
	ds_read_b128 v[196:199], v139 offset:37888
	ds_read_b128 v[200:203], v139 offset:38912
	ds_read_b128 v[204:207], v139 offset:39936
	global_load_lds_dwordx4 v132, s[22:23]
	s_mov_b32 m0, s46
	s_nop 0
	global_load_lds_dwordx4 v130, s[22:23]
	s_waitcnt vmcnt(8)
	s_waitcnt lgkmcnt(0)
	s_barrier
	s_setprio 1
	s_waitcnt lgkmcnt(0)
	v_mfma_f32_16x16x32_bf16 v[124:127], v[140:143], v[172:175], v[124:127]
	v_mfma_f32_16x16x32_bf16 v[120:123], v[148:151], v[172:175], v[120:123]
	v_mfma_f32_16x16x32_bf16 v[116:119], v[140:143], v[184:187], v[116:119]
	v_mfma_f32_16x16x32_bf16 v[112:115], v[148:151], v[184:187], v[112:115]
	v_mfma_f32_16x16x32_bf16 v[92:95], v[140:143], v[192:195], v[92:95]
	v_mfma_f32_16x16x32_bf16 v[88:91], v[148:151], v[192:195], v[88:91]
	v_mfma_f32_16x16x32_bf16 v[80:83], v[140:143], v[200:203], v[80:83]
	v_mfma_f32_16x16x32_bf16 v[72:75], v[148:151], v[200:203], v[72:75]
	v_mfma_f32_16x16x32_bf16 v[124:127], v[144:147], v[176:179], v[124:127]
	v_mfma_f32_16x16x32_bf16 v[120:123], v[152:155], v[176:179], v[120:123]
	v_mfma_f32_16x16x32_bf16 v[116:119], v[144:147], v[188:191], v[116:119]
	v_mfma_f32_16x16x32_bf16 v[112:115], v[152:155], v[188:191], v[112:115]
	v_mfma_f32_16x16x32_bf16 v[92:95], v[144:147], v[196:199], v[92:95]
	v_mfma_f32_16x16x32_bf16 v[88:91], v[152:155], v[196:199], v[88:91]
	v_mfma_f32_16x16x32_bf16 v[80:83], v[144:147], v[204:207], v[80:83]
	v_mfma_f32_16x16x32_bf16 v[72:75], v[152:155], v[204:207], v[72:75]
	s_setprio 0
	s_setprio 1
	v_mfma_f32_16x16x32_bf16 v[108:111], v[156:159], v[172:175], v[108:111]
	v_mfma_f32_16x16x32_bf16 v[104:107], v[164:167], v[172:175], v[104:107]
	v_mfma_f32_16x16x32_bf16 v[100:103], v[156:159], v[184:187], v[100:103]
	v_mfma_f32_16x16x32_bf16 v[96:99], v[164:167], v[184:187], v[96:99]
	v_mfma_f32_16x16x32_bf16 v[84:87], v[156:159], v[192:195], v[84:87]
	v_mfma_f32_16x16x32_bf16 v[76:79], v[164:167], v[192:195], v[76:79]
	v_mfma_f32_16x16x32_bf16 v[68:71], v[156:159], v[200:203], v[68:71]
	v_mfma_f32_16x16x32_bf16 v[64:67], v[164:167], v[200:203], v[64:67]
	v_mfma_f32_16x16x32_bf16 v[108:111], v[160:163], v[176:179], v[108:111]
	v_mfma_f32_16x16x32_bf16 v[104:107], v[168:171], v[176:179], v[104:107]
	v_mfma_f32_16x16x32_bf16 v[100:103], v[160:163], v[188:191], v[100:103]
	v_mfma_f32_16x16x32_bf16 v[96:99], v[168:171], v[188:191], v[96:99]
	v_mfma_f32_16x16x32_bf16 v[84:87], v[160:163], v[196:199], v[84:87]
	v_mfma_f32_16x16x32_bf16 v[76:79], v[168:171], v[196:199], v[76:79]
	v_mfma_f32_16x16x32_bf16 v[68:71], v[160:163], v[204:207], v[68:71]
	v_mfma_f32_16x16x32_bf16 v[64:67], v[168:171], v[204:207], v[64:67]
	s_setprio 0
	s_barrier
	s_add_i32 s22, s55, s42
	s_mov_b32 m0, s22
	ds_read_b128 v[172:175], v139 offset:49152
	ds_read_b128 v[176:179], v139 offset:50176
	ds_read_b128 v[184:187], v139 offset:51200
	ds_read_b128 v[188:191], v139 offset:52224
	ds_read_b128 v[192:195], v139 offset:53248
	ds_read_b128 v[196:199], v139 offset:54272
	ds_read_b128 v[200:203], v139 offset:55296
	ds_read_b128 v[204:207], v139 offset:56320
	global_load_lds_dwordx4 v212, s[84:85]
	s_add_i32 m0, s22, 0x2000
	s_add_u32 s20, s20, 0x100080
	s_addc_u32 s21, s21, 0
	s_add_i32 s22, s56, s42
	global_load_lds_dwordx4 v128, s[84:85]


	s_waitcnt vmcnt(4)
	s_waitcnt lgkmcnt(0)
	s_barrier
	s_setprio 1
	s_waitcnt lgkmcnt(0)
	v_mfma_f32_16x16x32_bf16 v[60:63], v[140:143], v[172:175], v[60:63]
	v_mfma_f32_16x16x32_bf16 v[56:59], v[148:151], v[172:175], v[56:59]
	v_mfma_f32_16x16x32_bf16 v[48:51], v[140:143], v[184:187], v[48:51]
	v_mfma_f32_16x16x32_bf16 v[40:43], v[148:151], v[184:187], v[40:43]
	s_mov_b32 m0, s22
	v_mfma_f32_16x16x32_bf16 v[28:31], v[140:143], v[192:195], v[28:31]
	global_load_lds_dwordx4 v212, s[20:21]
	v_mfma_f32_16x16x32_bf16 v[24:27], v[148:151], v[192:195], v[24:27]
	v_mfma_f32_16x16x32_bf16 v[16:19], v[140:143], v[200:203], v[16:19]
	v_mfma_f32_16x16x32_bf16 v[8:11], v[148:151], v[200:203], v[8:11]
	v_mfma_f32_16x16x32_bf16 v[60:63], v[144:147], v[176:179], v[60:63]
	v_mfma_f32_16x16x32_bf16 v[56:59], v[152:155], v[176:179], v[56:59]
	v_mfma_f32_16x16x32_bf16 v[48:51], v[144:147], v[188:191], v[48:51]
	v_mfma_f32_16x16x32_bf16 v[40:43], v[152:155], v[188:191], v[40:43]
	s_add_i32 m0, s22, 0x2000
	v_mfma_f32_16x16x32_bf16 v[28:31], v[144:147], v[196:199], v[28:31]
	global_load_lds_dwordx4 v128, s[20:21]
	v_mfma_f32_16x16x32_bf16 v[24:27], v[152:155], v[196:199], v[24:27]
	v_mfma_f32_16x16x32_bf16 v[16:19], v[144:147], v[204:207], v[16:19]
	v_mfma_f32_16x16x32_bf16 v[8:11], v[152:155], v[204:207], v[8:11]
	s_setprio 0
	s_setprio 1
	v_mfma_f32_16x16x32_bf16 v[52:55], v[156:159], v[172:175], v[52:55]
	v_mfma_f32_16x16x32_bf16 v[44:47], v[164:167], v[172:175], v[44:47]
	v_mfma_f32_16x16x32_bf16 v[36:39], v[156:159], v[184:187], v[36:39]
	v_mfma_f32_16x16x32_bf16 v[32:35], v[164:167], v[184:187], v[32:35]
	s_mov_b32 m0, s48
	v_mfma_f32_16x16x32_bf16 v[20:23], v[156:159], v[192:195], v[20:23]
	global_load_lds_dwordx4 v132, s[86:87]
	v_mfma_f32_16x16x32_bf16 v[12:15], v[164:167], v[192:195], v[12:15]
	v_mfma_f32_16x16x32_bf16 v[4:7], v[156:159], v[200:203], v[4:7]
	v_mfma_f32_16x16x32_bf16 v[0:3], v[164:167], v[200:203], v[0:3]
	v_mfma_f32_16x16x32_bf16 v[52:55], v[160:163], v[176:179], v[52:55]
	v_mfma_f32_16x16x32_bf16 v[44:47], v[168:171], v[176:179], v[44:47]
	v_mfma_f32_16x16x32_bf16 v[36:39], v[160:163], v[188:191], v[36:39]
	v_mfma_f32_16x16x32_bf16 v[32:35], v[168:171], v[188:191], v[32:35]
	s_mov_b32 m0, s49
	v_mfma_f32_16x16x32_bf16 v[20:23], v[160:163], v[196:199], v[20:23]
	global_load_lds_dwordx4 v130, s[86:87]
	v_mfma_f32_16x16x32_bf16 v[12:15], v[168:171], v[196:199], v[12:15]
	v_mfma_f32_16x16x32_bf16 v[4:7], v[160:163], v[204:207], v[4:7]
	v_mfma_f32_16x16x32_bf16 v[0:3], v[168:171], v[204:207], v[0:3]
	s_setprio 0
	s_barrier
	s_add_i32 s54, s54, 2
	s_add_u32 s18, s18, 0x100
	s_addc_u32 s19, s19, 0
	s_cmp_lt_u32 s54, 62
	s_cbranch_scc1 .LBB0_599
	s_waitcnt vmcnt(0)
	s_cmpk_gt_u32 s36, 0xff
	s_cbranch_scc1 .LBB0_602
	s_barrier
